# phase-0 weight conversion also processes tile pairs per iteration
# baseline (speedup 1.0000x reference)
.LBB0_43:
	v_lshrrev_b32_e32 v194, 4, v146
	s_lshl_b32 s84, s2, 1
	s_lshl_b32 s85, s3, 1
	s_cmpk_gt_i32 s84, 0x83f
	v_lshrrev_b32_e32 v128, 3, v146
	s_cbranch_scc1 .LBB0_58
	s_add_i32 s0, s84, 0x580
	s_cmpk_lt_i32 s84, 0x580
	s_cselect_b32 s1, s84, s0
	s_cmpk_gt_i32 s1, 0xaff
	s_cbranch_scc0 .LBB0_47
	s_add_i32 s0, s1, 0xf500
	s_and_b32 s4, s0, 0xffff
	s_mul_i32 s4, s4, 0xba2f
	s_lshr_b32 s4, s4, 21
	s_mul_i32 s5, s4, 44
	s_sub_i32 s0, s0, s5
	s_lshl_b32 s0, s0, 6
	s_lshl_b32 s16, s4, 6
	s_and_b32 s0, s0, 0xffc0
	s_mov_b64 s[6:7], s[40:41]
	s_movk_i32 s20, 0xb00
	s_cbranch_execz .LBB0_48
	s_mov_b64 s[8:9], 0x400
	s_mov_b64 s[4:5], 0x1600000
	s_mov_b32 s14, s16
	s_branch .LBB0_49

.LBB0_49:
	s_mov_b32 s1, 0
	s_mul_i32 s18, s8, s0
	s_mov_b32 s19, s1
	s_lshl_b64 s[18:19], s[18:19], 2
	s_add_u32 s9, s6, s18
	s_addc_u32 s17, s7, s19
	s_ashr_i32 s15, s14, 31
	s_lshl_b64 s[6:7], s[14:15], 2
	v_add_u32_e32 v1, 32, v194
	s_add_u32 s6, s9, s6
	v_mul_u32_u24_e32 v2, s8, v1
	s_addc_u32 s7, s17, s7
	v_lshlrev_b32_e32 v10, 2, v2
	v_mov_b32_e32 v11, 0
	v_and_b32_e32 v12, 60, v164
	v_lshl_add_u64 v[2:3], s[6:7], 0, v[10:11]
	v_lshlrev_b32_e32 v10, 2, v12
	v_lshl_add_u64 v[14:15], v[2:3], 0, v[10:11]
	v_mul_u32_u24_e32 v2, s8, v194
	v_lshlrev_b32_e32 v2, 2, v2
	v_mov_b32_e32 v3, v11
	v_lshl_add_u64 v[2:3], s[6:7], 0, v[2:3]
	v_lshl_add_u64 v[16:17], v[2:3], 0, v[10:11]
	global_load_dwordx4 v[6:9], v[14:15], off
	global_load_dwordx4 v[2:5], v[16:17], off
	s_lshl_b32 s86, s8, 8
	s_mov_b32 s87, 0
	v_lshl_add_u64 v[60:61], v[14:15], 0, s[86:87]
	v_lshl_add_u64 v[62:63], v[16:17], 0, s[86:87]
	global_load_dwordx4 v[36:39], v[60:61], off
	global_load_dwordx4 v[32:35], v[62:63], off
	s_add_u32 s6, s34, s4
	s_addc_u32 s7, s35, s5
	s_mul_hi_i32 s5, s20, s16
	s_mul_i32 s4, s20, s16
	v_mul_u32_u24_e32 v13, 0x104, v194
	s_lshl_b64 s[4:5], s[4:5], 1
	v_add3_u32 v16, 0, v13, v10
	v_lshlrev_b32_e32 v10, 3, v146
	s_add_u32 s6, s6, s4
	v_and_b32_e32 v10, 56, v10
	s_addc_u32 s7, s7, s5
	s_lshl_b64 s[4:5], s[0:1], 1
	v_mul_u32_u24_e32 v13, 0x104, v10
	v_lshlrev_b32_e32 v14, 2, v128
	s_add_u32 s4, s6, s4
	v_add3_u32 v17, 0, v13, v14
	s_addc_u32 s5, s7, s5
	v_add_u32_e32 v18, 0x2080, v16
	v_add_u32_e32 v19, 0x2088, v16
	v_add_u32_e32 v40, 0x4100, v16
	v_add_u32_e32 v41, 0x6180, v16
	v_add_u32_e32 v42, 0x6188, v16
	v_lshlrev_b32_e32 v12, 2, v12
	v_lshlrev_b32_e32 v14, 1, v10
	v_add_u32_e32 v20, 0x400, v17
	v_add_u32_e32 v43, 0x4100, v17
	v_add_u32_e32 v44, 0x4500, v17
	v_mov_b32_e32 v15, v11
	s_mov_b32 s21, s84
	s_branch .LBB0_53

.LBB0_51:
	s_add_u32 s15, s34, s18
	s_addc_u32 s24, s35, s19
	s_mul_i32 s18, s14, s0
	s_mov_b32 s19, s1
	s_ashr_i32 s17, s16, 31
	s_lshl_b64 s[18:19], s[18:19], 2
	s_add_u32 s18, s8, s18
	s_addc_u32 s19, s9, s19
	s_lshl_b64 s[8:9], s[16:17], 2
	s_add_u32 s8, s18, s8
	v_mul_u32_u24_e32 v2, s14, v194
	s_addc_u32 s9, s19, s9
	v_lshlrev_b32_e32 v10, 2, v2
	v_mul_u32_u24_e32 v4, s14, v1
	v_lshl_add_u64 v[2:3], s[8:9], 0, v[10:11]
	v_lshlrev_b32_e32 v10, 2, v4
	v_mov_b32_e32 v13, v11
	v_lshl_add_u64 v[4:5], s[8:9], 0, v[10:11]
	v_lshl_add_u64 v[2:3], v[2:3], 0, v[12:13]
	v_lshl_add_u64 v[6:7], v[4:5], 0, v[12:13]
	s_lshl_b32 s86, s14, 8
	s_mov_b32 s87, 0
	v_lshl_add_u64 v[60:61], v[2:3], 0, s[86:87]
	v_lshl_add_u64 v[62:63], v[6:7], 0, s[86:87]
	global_load_dwordx4 v[2:5], v[2:3], off
	s_nop 0
	global_load_dwordx4 v[6:9], v[6:7], off
	global_load_dwordx4 v[32:35], v[60:61], off
	global_load_dwordx4 v[36:39], v[62:63], off
	s_mul_hi_i32 s9, s22, s23
	s_mul_i32 s8, s22, s23
	s_lshl_b64 s[8:9], s[8:9], 1
	s_add_u32 s14, s15, s8
	s_addc_u32 s15, s24, s9
	s_lshl_b64 s[8:9], s[0:1], 1
	s_add_u32 s8, s14, s8
	s_addc_u32 s9, s15, s9
.LBB0_52:
	s_waitcnt lgkmcnt(0)
	s_barrier
	ds_read2_b32 v[22:23], v17 offset1:65
	ds_read2_b32 v[24:25], v17 offset0:130 offset1:195
	ds_read2_b32 v[26:27], v20 offset0:4 offset1:69
	ds_read2_b32 v[28:29], v20 offset0:134 offset1:199
	ds_read2_b32 v[48:49], v43 offset1:65
	ds_read2_b32 v[50:51], v43 offset0:130 offset1:195
	ds_read2_b32 v[52:53], v44 offset0:4 offset1:69
	ds_read2_b32 v[54:55], v44 offset0:134 offset1:199
	s_and_b64 vcc, exec, s[6:7]
	s_waitcnt lgkmcnt(7)
	v_cvt_pk_bf16_f32 v22, v22, v23
	s_waitcnt lgkmcnt(6)
	v_cvt_pk_bf16_f32 v23, v24, v25
	s_waitcnt lgkmcnt(5)
	v_cvt_pk_bf16_f32 v24, v26, v27
	v_mad_u64_u32 v[26:27], s[14:15], s20, v128, 0
	v_lshl_add_u64 v[26:27], v[26:27], 1, s[4:5]
	s_waitcnt lgkmcnt(4)
	v_cvt_pk_bf16_f32 v25, v28, v29
	v_lshl_add_u64 v[26:27], v[26:27], 0, v[14:15]
	global_store_dwordx4 v[26:27], v[22:25], off
	s_waitcnt lgkmcnt(3)
	v_cvt_pk_bf16_f32 v56, v48, v49
	s_waitcnt lgkmcnt(2)
	v_cvt_pk_bf16_f32 v57, v50, v51
	s_waitcnt lgkmcnt(1)
	v_cvt_pk_bf16_f32 v58, v52, v53
	s_waitcnt lgkmcnt(0)
	v_cvt_pk_bf16_f32 v59, v54, v55
	global_store_dwordx4 v[26:27], v[56:59], off offset:128
	s_waitcnt lgkmcnt(0)
	s_barrier
	s_mov_b64 s[4:5], s[8:9]
	s_mov_b32 s20, s22
	s_cbranch_vccnz .LBB0_58
.LBB0_53:
	s_add_i32 s21, s21, s85
	s_cmpk_gt_i32 s21, 0x83f
	s_cselect_b64 s[6:7], -1, 0
	s_mov_b64 s[8:9], 0
	s_and_b64 vcc, exec, s[6:7]
	s_mov_b32 s22, 0
	s_waitcnt vmcnt(0)
	ds_write2_b32 v16, v2, v3 offset1:1
	ds_write2_b32 v18, v6, v7 offset1:1
	ds_write2_b32 v16, v4, v5 offset0:2 offset1:3
	ds_write2_b32 v19, v8, v9 offset1:1
	ds_write2_b32 v40, v32, v33 offset1:1
	ds_write2_b32 v41, v36, v37 offset1:1
	ds_write2_b32 v40, v34, v35 offset0:2 offset1:3
	ds_write2_b32 v42, v38, v39 offset1:1
	s_cbranch_vccnz .LBB0_52
	s_add_i32 s0, s21, 0x580
	s_cmpk_lt_i32 s21, 0x580
	s_cselect_b32 s17, s21, s0
	s_cmpk_gt_i32 s17, 0xaff
	s_mov_b64 s[14:15], -1
	s_cbranch_scc0 .LBB0_56
	s_add_i32 s0, s17, 0xf500
	s_and_b32 s8, s0, 0xffff
	s_mul_i32 s8, s8, 0xba2f
	s_lshr_b32 s8, s8, 21
	s_mul_i32 s9, s8, 44
	s_sub_i32 s0, s0, s9
	s_lshl_b32 s0, s0, 6
	s_lshl_b32 s23, s8, 6
	s_and_b32 s0, s0, 0xffc0
	s_mov_b64 s[14:15], 0
	s_mov_b64 s[8:9], s[40:41]
